# scalar-side LDS-DMA addressing extended to the two out-GEMM (LN) K-loops (14 of 16 adds; the vcc-based pair stays)
# baseline (speedup 1.0000x reference)
.LBB0_1145:
	v_add_u32_e32 v157, s67, v146
	ds_read_b128 v[148:151], v157
	ds_read_b128 v[152:155], v157 offset:1024
	ds_read_b128 v[186:189], v157 offset:2048
	ds_read_b128 v[190:193], v157 offset:3072
	v_add_u32_e32 v157, s68, v146
	s_add_u32 s28, s54, vcc_lo
	ds_read_b128 v[194:197], v157
	ds_read_b128 v[198:201], v157 offset:1024
	ds_read_b128 v[202:205], v157 offset:2048
	ds_read_b128 v[206:209], v157 offset:3072
	s_addc_u32 s29, s55, vcc_hi
	s_add_u32 s28, s28, 0x100
	s_addc_u32 s29, s29, 0
	s_add_u32 s30, s19, vcc_lo
	s_addc_u32 s31, s20, vcc_hi
	s_cmpk_eq_i32 vcc_lo, 0x700
	s_cselect_b32 s61, s21, s29
	s_cselect_b32 s60, s24, s28
	s_cselect_b32 s31, s25, s31
	s_cselect_b32 s30, s26, s30
	v_lshl_add_u64 v[168:169], v[140:141], 0, vcc
	s_add_i32 m0, s10, 0xc000
	ds_read_b128 v[210:213], v147
	ds_read_b128 v[214:217], v147 offset:1024
	ds_read_b128 v[218:221], v147 offset:2048
	ds_read_b128 v[222:225], v147 offset:3072
	ds_read_b128 v[226:229], v147 offset:4096
	ds_read_b128 v[230:233], v147 offset:5120
	ds_read_b128 v[234:237], v147 offset:6144
	ds_read_b128 v[238:241], v147 offset:7168
	global_load_lds_dwordx4 v[168:169], off
	v_lshl_add_u64 v[168:169], v[142:143], 0, vcc
	s_add_i32 m0, s10, 0xe000
	s_nop 0
	global_load_lds_dwordx4 v[168:169], off
	s_waitcnt vmcnt(8)
	s_waitcnt lgkmcnt(0)
	v_mfma_f32_16x16x32_bf16 v[36:39], v[148:151], v[210:213], v[36:39]
	v_mfma_f32_16x16x32_bf16 v[20:23], v[186:189], v[210:213], v[20:23]
	v_mfma_f32_16x16x32_bf16 v[40:43], v[148:151], v[218:221], v[40:43]
	v_mfma_f32_16x16x32_bf16 v[24:27], v[186:189], v[218:221], v[24:27]
	s_barrier
	s_setprio 1
	s_waitcnt lgkmcnt(0)
	v_mfma_f32_16x16x32_bf16 v[100:103], v[148:151], v[226:229], v[100:103]
	v_mfma_f32_16x16x32_bf16 v[84:87], v[186:189], v[226:229], v[84:87]
	v_mfma_f32_16x16x32_bf16 v[104:107], v[148:151], v[234:237], v[104:107]
	v_mfma_f32_16x16x32_bf16 v[88:91], v[186:189], v[234:237], v[88:91]
	v_mfma_f32_16x16x32_bf16 v[36:39], v[152:155], v[214:217], v[36:39]
	v_mfma_f32_16x16x32_bf16 v[20:23], v[190:193], v[214:217], v[20:23]
	v_mfma_f32_16x16x32_bf16 v[40:43], v[152:155], v[222:225], v[40:43]
	v_mfma_f32_16x16x32_bf16 v[24:27], v[190:193], v[222:225], v[24:27]
	v_mfma_f32_16x16x32_bf16 v[100:103], v[152:155], v[230:233], v[100:103]
	v_mfma_f32_16x16x32_bf16 v[84:87], v[190:193], v[230:233], v[84:87]
	v_mfma_f32_16x16x32_bf16 v[104:107], v[152:155], v[238:241], v[104:107]
	v_mfma_f32_16x16x32_bf16 v[88:91], v[190:193], v[238:241], v[88:91]
	s_setprio 0
	s_setprio 1
	v_mfma_f32_16x16x32_bf16 v[12:15], v[194:197], v[210:213], v[12:15]
	v_mfma_f32_16x16x32_bf16 v[4:7], v[202:205], v[210:213], v[4:7]
	v_mfma_f32_16x16x32_bf16 v[16:19], v[194:197], v[218:221], v[16:19]
	v_mfma_f32_16x16x32_bf16 v[8:11], v[202:205], v[218:221], v[8:11]
	v_mfma_f32_16x16x32_bf16 v[64:67], v[194:197], v[226:229], v[64:67]
	v_mfma_f32_16x16x32_bf16 v[32:35], v[202:205], v[226:229], v[32:35]
	v_mfma_f32_16x16x32_bf16 v[68:71], v[194:197], v[234:237], v[68:71]
	v_mfma_f32_16x16x32_bf16 v[28:31], v[202:205], v[234:237], v[28:31]
	v_mfma_f32_16x16x32_bf16 v[12:15], v[198:201], v[214:217], v[12:15]
	v_mfma_f32_16x16x32_bf16 v[4:7], v[206:209], v[214:217], v[4:7]
	v_mfma_f32_16x16x32_bf16 v[16:19], v[198:201], v[222:225], v[16:19]
	v_mfma_f32_16x16x32_bf16 v[8:11], v[206:209], v[222:225], v[8:11]
	v_mfma_f32_16x16x32_bf16 v[64:67], v[198:201], v[230:233], v[64:67]
	v_mfma_f32_16x16x32_bf16 v[32:35], v[206:209], v[230:233], v[32:35]
	v_mfma_f32_16x16x32_bf16 v[68:71], v[198:201], v[238:241], v[68:71]
	v_mfma_f32_16x16x32_bf16 v[28:31], v[206:209], v[238:241], v[28:31]
	s_setprio 0
	s_barrier
	s_add_i32 s28, s67, s9
	s_mov_b32 m0, s28
	ds_read_b128 v[210:213], v147 offset:16384
	ds_read_b128 v[214:217], v147 offset:17408
	ds_read_b128 v[218:221], v147 offset:18432
	ds_read_b128 v[222:225], v147 offset:19456
	ds_read_b128 v[226:229], v147 offset:20480
	ds_read_b128 v[230:233], v147 offset:21504
	ds_read_b128 v[234:237], v147 offset:22528
	ds_read_b128 v[238:241], v147 offset:23552
	global_load_lds_dwordx4 v2, s[30:31]
	s_add_i32 m0, s28, 0x2000
	s_add_i32 s28, s68, s9
	global_load_lds_dwordx4 v0, s[30:31]
	s_mov_b32 m0, s28
	s_nop 0
	global_load_lds_dwordx4 v134, s[30:31]
	s_add_i32 m0, s28, 0x2000
	s_nop 0
	global_load_lds_dwordx4 v132, s[30:31]
	s_mov_b32 m0, s10
	s_nop 0
	global_load_lds_dwordx4 v2, s[60:61]
	s_mov_b32 m0, s11
	s_nop 0
	global_load_lds_dwordx4 v0, s[60:61]
	s_waitcnt vmcnt(8)
	s_waitcnt lgkmcnt(0)
	v_mfma_f32_16x16x32_bf16 v[128:131], v[148:151], v[210:213], v[128:131]
	v_mfma_f32_16x16x32_bf16 v[124:127], v[186:189], v[210:213], v[124:127]
	v_mfma_f32_16x16x32_bf16 v[120:123], v[148:151], v[218:221], v[120:123]
	v_mfma_f32_16x16x32_bf16 v[116:119], v[186:189], v[218:221], v[116:119]
	s_barrier
	s_setprio 1
	s_waitcnt lgkmcnt(0)
	v_mfma_f32_16x16x32_bf16 v[80:83], v[148:151], v[226:229], v[80:83]
	v_mfma_f32_16x16x32_bf16 v[76:79], v[186:189], v[226:229], v[76:79]
	v_mfma_f32_16x16x32_bf16 v[72:75], v[148:151], v[234:237], v[72:75]
	v_mfma_f32_16x16x32_bf16 v[60:63], v[186:189], v[234:237], v[60:63]
	v_mfma_f32_16x16x32_bf16 v[128:131], v[152:155], v[214:217], v[128:131]
	v_mfma_f32_16x16x32_bf16 v[124:127], v[190:193], v[214:217], v[124:127]
	v_mfma_f32_16x16x32_bf16 v[120:123], v[152:155], v[222:225], v[120:123]
	v_mfma_f32_16x16x32_bf16 v[116:119], v[190:193], v[222:225], v[116:119]
	v_mfma_f32_16x16x32_bf16 v[80:83], v[152:155], v[230:233], v[80:83]
	v_mfma_f32_16x16x32_bf16 v[76:79], v[190:193], v[230:233], v[76:79]
	v_mfma_f32_16x16x32_bf16 v[72:75], v[152:155], v[238:241], v[72:75]
	v_mfma_f32_16x16x32_bf16 v[60:63], v[190:193], v[238:241], v[60:63]
	s_setprio 0
	s_setprio 1
	v_mfma_f32_16x16x32_bf16 v[108:111], v[194:197], v[210:213], v[108:111]
	v_mfma_f32_16x16x32_bf16 v[92:95], v[202:205], v[210:213], v[92:95]
	v_mfma_f32_16x16x32_bf16 v[112:115], v[194:197], v[218:221], v[112:115]
	v_mfma_f32_16x16x32_bf16 v[96:99], v[202:205], v[218:221], v[96:99]
	v_mfma_f32_16x16x32_bf16 v[56:59], v[194:197], v[226:229], v[56:59]
	v_mfma_f32_16x16x32_bf16 v[52:55], v[202:205], v[226:229], v[52:55]
	v_mfma_f32_16x16x32_bf16 v[48:51], v[194:197], v[234:237], v[48:51]
	v_mfma_f32_16x16x32_bf16 v[44:47], v[202:205], v[234:237], v[44:47]
	v_mfma_f32_16x16x32_bf16 v[108:111], v[198:201], v[214:217], v[108:111]
	v_mfma_f32_16x16x32_bf16 v[92:95], v[206:209], v[214:217], v[92:95]
	v_mfma_f32_16x16x32_bf16 v[112:115], v[198:201], v[222:225], v[112:115]
	v_mfma_f32_16x16x32_bf16 v[96:99], v[206:209], v[222:225], v[96:99]
	v_mfma_f32_16x16x32_bf16 v[56:59], v[198:201], v[230:233], v[56:59]
	v_mfma_f32_16x16x32_bf16 v[52:55], v[206:209], v[230:233], v[52:55]
	v_mfma_f32_16x16x32_bf16 v[48:51], v[198:201], v[238:241], v[48:51]
	v_mfma_f32_16x16x32_bf16 v[44:47], v[206:209], v[238:241], v[44:47]
	s_setprio 0
	s_barrier
	v_add_u32_e32 v157, s82, v146
	ds_read_b128 v[148:151], v157
	ds_read_b128 v[152:155], v157 offset:1024
	ds_read_b128 v[186:189], v157 offset:2048
	ds_read_b128 v[190:193], v157 offset:3072
	v_add_u32_e32 v157, s62, v146
	ds_read_b128 v[194:197], v157
	ds_read_b128 v[198:201], v157 offset:1024
	ds_read_b128 v[202:205], v157 offset:2048
	ds_read_b128 v[206:209], v157 offset:3072
	s_add_u32 s60, s60, 0x40000
	s_addc_u32 s61, s61, 0
	s_mov_b32 m0, s12
	ds_read_b128 v[210:213], v147 offset:32768
	ds_read_b128 v[214:217], v147 offset:33792
	ds_read_b128 v[218:221], v147 offset:34816
	ds_read_b128 v[222:225], v147 offset:35840
	ds_read_b128 v[226:229], v147 offset:36864
	ds_read_b128 v[230:233], v147 offset:37888
	ds_read_b128 v[234:237], v147 offset:38912
	ds_read_b128 v[238:241], v147 offset:39936
	global_load_lds_dwordx4 v2, s[60:61]
	s_mov_b32 m0, s13
	s_nop 0
	global_load_lds_dwordx4 v0, s[60:61]
	s_waitcnt vmcnt(8)
	s_waitcnt lgkmcnt(0)
	v_mfma_f32_16x16x32_bf16 v[36:39], v[148:151], v[210:213], v[36:39]
	v_mfma_f32_16x16x32_bf16 v[20:23], v[186:189], v[210:213], v[20:23]
	v_mfma_f32_16x16x32_bf16 v[40:43], v[148:151], v[218:221], v[40:43]
	v_mfma_f32_16x16x32_bf16 v[24:27], v[186:189], v[218:221], v[24:27]
	s_barrier
	s_setprio 1
	s_waitcnt lgkmcnt(0)
	v_mfma_f32_16x16x32_bf16 v[100:103], v[148:151], v[226:229], v[100:103]
	v_mfma_f32_16x16x32_bf16 v[84:87], v[186:189], v[226:229], v[84:87]
	v_mfma_f32_16x16x32_bf16 v[104:107], v[148:151], v[234:237], v[104:107]
	v_mfma_f32_16x16x32_bf16 v[88:91], v[186:189], v[234:237], v[88:91]
	v_mfma_f32_16x16x32_bf16 v[36:39], v[152:155], v[214:217], v[36:39]
	v_mfma_f32_16x16x32_bf16 v[20:23], v[190:193], v[214:217], v[20:23]
	v_mfma_f32_16x16x32_bf16 v[40:43], v[152:155], v[222:225], v[40:43]
	v_mfma_f32_16x16x32_bf16 v[24:27], v[190:193], v[222:225], v[24:27]
	v_mfma_f32_16x16x32_bf16 v[100:103], v[152:155], v[230:233], v[100:103]
	v_mfma_f32_16x16x32_bf16 v[84:87], v[190:193], v[230:233], v[84:87]
	v_mfma_f32_16x16x32_bf16 v[104:107], v[152:155], v[238:241], v[104:107]
	v_mfma_f32_16x16x32_bf16 v[88:91], v[190:193], v[238:241], v[88:91]
	s_setprio 0
	s_setprio 1
	v_mfma_f32_16x16x32_bf16 v[12:15], v[194:197], v[210:213], v[12:15]
	v_mfma_f32_16x16x32_bf16 v[4:7], v[202:205], v[210:213], v[4:7]
	v_mfma_f32_16x16x32_bf16 v[16:19], v[194:197], v[218:221], v[16:19]
	v_mfma_f32_16x16x32_bf16 v[8:11], v[202:205], v[218:221], v[8:11]
	v_mfma_f32_16x16x32_bf16 v[64:67], v[194:197], v[226:229], v[64:67]
	v_mfma_f32_16x16x32_bf16 v[32:35], v[202:205], v[226:229], v[32:35]
	v_mfma_f32_16x16x32_bf16 v[68:71], v[194:197], v[234:237], v[68:71]
	v_mfma_f32_16x16x32_bf16 v[28:31], v[202:205], v[234:237], v[28:31]
	v_mfma_f32_16x16x32_bf16 v[12:15], v[198:201], v[214:217], v[12:15]
	v_mfma_f32_16x16x32_bf16 v[4:7], v[206:209], v[214:217], v[4:7]
	v_mfma_f32_16x16x32_bf16 v[16:19], v[198:201], v[222:225], v[16:19]
	v_mfma_f32_16x16x32_bf16 v[8:11], v[206:209], v[222:225], v[8:11]
	v_mfma_f32_16x16x32_bf16 v[64:67], v[198:201], v[230:233], v[64:67]
	v_mfma_f32_16x16x32_bf16 v[32:35], v[206:209], v[230:233], v[32:35]
	v_mfma_f32_16x16x32_bf16 v[68:71], v[198:201], v[238:241], v[68:71]
	v_mfma_f32_16x16x32_bf16 v[28:31], v[206:209], v[238:241], v[28:31]
	s_setprio 0
	s_barrier
	s_add_i32 s28, s82, s9
	s_add_u32 s30, s30, 0x80
	s_addc_u32 s31, s31, 0
	s_add_u32 s60, s60, 0xfffc0080
	s_addc_u32 s61, s61, -1
	s_mov_b32 m0, s28
	ds_read_b128 v[210:213], v147 offset:49152
	ds_read_b128 v[214:217], v147 offset:50176
	ds_read_b128 v[218:221], v147 offset:51200
	ds_read_b128 v[222:225], v147 offset:52224
	ds_read_b128 v[226:229], v147 offset:53248
	ds_read_b128 v[230:233], v147 offset:54272
	ds_read_b128 v[234:237], v147 offset:55296
	ds_read_b128 v[238:241], v147 offset:56320
	global_load_lds_dwordx4 v2, s[30:31]
	s_add_i32 m0, s28, 0x2000
	s_add_i32 s28, s62, s9
	global_load_lds_dwordx4 v0, s[30:31]
	s_mov_b32 m0, s28
	s_nop 0
	global_load_lds_dwordx4 v134, s[30:31]
	s_add_i32 m0, s28, 0x2000
	s_nop 0
	global_load_lds_dwordx4 v132, s[30:31]
	s_mov_b32 m0, s15
	s_nop 0
	global_load_lds_dwordx4 v2, s[60:61]
	s_mov_b32 m0, s16
	s_nop 0
	global_load_lds_dwordx4 v0, s[60:61]
	s_waitcnt vmcnt(8)
	s_waitcnt lgkmcnt(0)
	v_mfma_f32_16x16x32_bf16 v[128:131], v[148:151], v[210:213], v[128:131]
	v_mfma_f32_16x16x32_bf16 v[124:127], v[186:189], v[210:213], v[124:127]
	v_mfma_f32_16x16x32_bf16 v[120:123], v[148:151], v[218:221], v[120:123]
	v_mfma_f32_16x16x32_bf16 v[116:119], v[186:189], v[218:221], v[116:119]
	s_barrier
	s_setprio 1
	s_waitcnt lgkmcnt(0)
	v_mfma_f32_16x16x32_bf16 v[80:83], v[148:151], v[226:229], v[80:83]
	v_mfma_f32_16x16x32_bf16 v[76:79], v[186:189], v[226:229], v[76:79]
	v_mfma_f32_16x16x32_bf16 v[72:75], v[148:151], v[234:237], v[72:75]
	v_mfma_f32_16x16x32_bf16 v[60:63], v[186:189], v[234:237], v[60:63]
	v_mfma_f32_16x16x32_bf16 v[128:131], v[152:155], v[214:217], v[128:131]
	v_mfma_f32_16x16x32_bf16 v[124:127], v[190:193], v[214:217], v[124:127]
	v_mfma_f32_16x16x32_bf16 v[120:123], v[152:155], v[222:225], v[120:123]
	v_mfma_f32_16x16x32_bf16 v[116:119], v[190:193], v[222:225], v[116:119]
	v_mfma_f32_16x16x32_bf16 v[80:83], v[152:155], v[230:233], v[80:83]
	v_mfma_f32_16x16x32_bf16 v[76:79], v[190:193], v[230:233], v[76:79]
	v_mfma_f32_16x16x32_bf16 v[72:75], v[152:155], v[238:241], v[72:75]
	v_mfma_f32_16x16x32_bf16 v[60:63], v[190:193], v[238:241], v[60:63]
	s_setprio 0
	s_setprio 1
	v_mfma_f32_16x16x32_bf16 v[108:111], v[194:197], v[210:213], v[108:111]
	v_mfma_f32_16x16x32_bf16 v[92:95], v[202:205], v[210:213], v[92:95]
	v_mfma_f32_16x16x32_bf16 v[112:115], v[194:197], v[218:221], v[112:115]
	v_mfma_f32_16x16x32_bf16 v[96:99], v[202:205], v[218:221], v[96:99]
	v_mfma_f32_16x16x32_bf16 v[56:59], v[194:197], v[226:229], v[56:59]
	v_mfma_f32_16x16x32_bf16 v[52:55], v[202:205], v[226:229], v[52:55]
	v_mfma_f32_16x16x32_bf16 v[48:51], v[194:197], v[234:237], v[48:51]
	v_mfma_f32_16x16x32_bf16 v[44:47], v[202:205], v[234:237], v[44:47]
	v_mfma_f32_16x16x32_bf16 v[108:111], v[198:201], v[214:217], v[108:111]
	v_mfma_f32_16x16x32_bf16 v[92:95], v[206:209], v[214:217], v[92:95]
	v_mfma_f32_16x16x32_bf16 v[112:115], v[198:201], v[222:225], v[112:115]
	v_mfma_f32_16x16x32_bf16 v[96:99], v[206:209], v[222:225], v[96:99]
	v_mfma_f32_16x16x32_bf16 v[56:59], v[198:201], v[230:233], v[56:59]
	v_mfma_f32_16x16x32_bf16 v[52:55], v[206:209], v[230:233], v[52:55]
	v_mfma_f32_16x16x32_bf16 v[48:51], v[198:201], v[238:241], v[48:51]
	v_mfma_f32_16x16x32_bf16 v[44:47], v[206:209], v[238:241], v[44:47]
	s_setprio 0
	s_barrier
	s_add_i32 s27, s27, 2
	s_add_u32 vcc_lo, vcc_lo, 0x100
	s_addc_u32 vcc_hi, vcc_hi, 0
	s_cmp_gt_u32 s27, 13
	s_cbranch_scc0 .LBB0_1145
	s_and_b64 vcc, exec, s[48:49]
	s_cbranch_vccz .LBB0_1148
	s_barrier

.LBB0_1201:
	v_add_u32_e32 v157, s67, v146
	ds_read_b128 v[148:151], v157
	ds_read_b128 v[152:155], v157 offset:1024
	ds_read_b128 v[186:189], v157 offset:2048
	ds_read_b128 v[190:193], v157 offset:3072
	v_add_u32_e32 v157, s68, v146
	s_add_u32 s28, s54, vcc_lo
	ds_read_b128 v[194:197], v157
	ds_read_b128 v[198:201], v157 offset:1024
	ds_read_b128 v[202:205], v157 offset:2048
	ds_read_b128 v[206:209], v157 offset:3072
	s_addc_u32 s29, s55, vcc_hi
	s_add_u32 s28, s28, 0x100
	s_addc_u32 s29, s29, 0
	s_add_u32 s30, s19, vcc_lo
	s_addc_u32 s31, s20, vcc_hi
	s_cmpk_eq_i32 vcc_lo, 0x700
	s_cselect_b32 s59, s21, s29
	s_cselect_b32 s58, s24, s28
	s_cselect_b32 s31, s25, s31
	s_cselect_b32 s30, s26, s30
	v_lshl_add_u64 v[168:169], v[140:141], 0, vcc
	s_add_i32 m0, s10, 0xc000
	ds_read_b128 v[210:213], v147
	ds_read_b128 v[214:217], v147 offset:1024
	ds_read_b128 v[218:221], v147 offset:2048
	ds_read_b128 v[222:225], v147 offset:3072
	ds_read_b128 v[226:229], v147 offset:4096
	ds_read_b128 v[230:233], v147 offset:5120
	ds_read_b128 v[234:237], v147 offset:6144
	ds_read_b128 v[238:241], v147 offset:7168
	global_load_lds_dwordx4 v[168:169], off
	v_lshl_add_u64 v[168:169], v[142:143], 0, vcc
	s_add_i32 m0, s10, 0xe000
	s_nop 0
	global_load_lds_dwordx4 v[168:169], off
	s_waitcnt vmcnt(8)
	s_waitcnt lgkmcnt(0)
	v_mfma_f32_16x16x32_bf16 v[36:39], v[148:151], v[210:213], v[36:39]
	v_mfma_f32_16x16x32_bf16 v[24:27], v[186:189], v[210:213], v[24:27]
	v_mfma_f32_16x16x32_bf16 v[40:43], v[148:151], v[218:221], v[40:43]
	v_mfma_f32_16x16x32_bf16 v[20:23], v[186:189], v[218:221], v[20:23]
	s_barrier
	s_setprio 1
	s_waitcnt lgkmcnt(0)
	v_mfma_f32_16x16x32_bf16 v[100:103], v[148:151], v[226:229], v[100:103]
	v_mfma_f32_16x16x32_bf16 v[88:91], v[186:189], v[226:229], v[88:91]
	v_mfma_f32_16x16x32_bf16 v[104:107], v[148:151], v[234:237], v[104:107]
	v_mfma_f32_16x16x32_bf16 v[84:87], v[186:189], v[234:237], v[84:87]
	v_mfma_f32_16x16x32_bf16 v[36:39], v[152:155], v[214:217], v[36:39]
	v_mfma_f32_16x16x32_bf16 v[24:27], v[190:193], v[214:217], v[24:27]
	v_mfma_f32_16x16x32_bf16 v[40:43], v[152:155], v[222:225], v[40:43]
	v_mfma_f32_16x16x32_bf16 v[20:23], v[190:193], v[222:225], v[20:23]
	v_mfma_f32_16x16x32_bf16 v[100:103], v[152:155], v[230:233], v[100:103]
	v_mfma_f32_16x16x32_bf16 v[88:91], v[190:193], v[230:233], v[88:91]
	v_mfma_f32_16x16x32_bf16 v[104:107], v[152:155], v[238:241], v[104:107]
	v_mfma_f32_16x16x32_bf16 v[84:87], v[190:193], v[238:241], v[84:87]
	s_setprio 0
	s_setprio 1
	v_mfma_f32_16x16x32_bf16 v[16:19], v[194:197], v[210:213], v[16:19]
	v_mfma_f32_16x16x32_bf16 v[8:11], v[202:205], v[210:213], v[8:11]
	v_mfma_f32_16x16x32_bf16 v[12:15], v[194:197], v[218:221], v[12:15]
	v_mfma_f32_16x16x32_bf16 v[4:7], v[202:205], v[218:221], v[4:7]
	v_mfma_f32_16x16x32_bf16 v[52:55], v[194:197], v[226:229], v[52:55]
	v_mfma_f32_16x16x32_bf16 v[32:35], v[202:205], v[226:229], v[32:35]
	v_mfma_f32_16x16x32_bf16 v[48:51], v[194:197], v[234:237], v[48:51]
	v_mfma_f32_16x16x32_bf16 v[28:31], v[202:205], v[234:237], v[28:31]
	v_mfma_f32_16x16x32_bf16 v[16:19], v[198:201], v[214:217], v[16:19]
	v_mfma_f32_16x16x32_bf16 v[8:11], v[206:209], v[214:217], v[8:11]
	v_mfma_f32_16x16x32_bf16 v[12:15], v[198:201], v[222:225], v[12:15]
	v_mfma_f32_16x16x32_bf16 v[4:7], v[206:209], v[222:225], v[4:7]
	v_mfma_f32_16x16x32_bf16 v[52:55], v[198:201], v[230:233], v[52:55]
	v_mfma_f32_16x16x32_bf16 v[32:35], v[206:209], v[230:233], v[32:35]
	v_mfma_f32_16x16x32_bf16 v[48:51], v[198:201], v[238:241], v[48:51]
	v_mfma_f32_16x16x32_bf16 v[28:31], v[206:209], v[238:241], v[28:31]
	s_setprio 0
	s_barrier
	s_add_i32 s28, s67, s9
	s_mov_b32 m0, s28
	ds_read_b128 v[210:213], v147 offset:16384
	ds_read_b128 v[214:217], v147 offset:17408
	ds_read_b128 v[218:221], v147 offset:18432
	ds_read_b128 v[222:225], v147 offset:19456
	ds_read_b128 v[226:229], v147 offset:20480
	ds_read_b128 v[230:233], v147 offset:21504
	ds_read_b128 v[234:237], v147 offset:22528
	ds_read_b128 v[238:241], v147 offset:23552
	global_load_lds_dwordx4 v2, s[30:31]
	s_add_i32 m0, s28, 0x2000
	s_add_i32 s28, s68, s9
	global_load_lds_dwordx4 v132, s[30:31]
	s_mov_b32 m0, s28
	s_nop 0
	global_load_lds_dwordx4 v134, s[30:31]
	s_add_i32 m0, s28, 0x2000
	s_nop 0
	global_load_lds_dwordx4 v0, s[30:31]
	s_mov_b32 m0, s10
	s_nop 0
	global_load_lds_dwordx4 v2, s[58:59]
	s_mov_b32 m0, s11
	s_nop 0
	global_load_lds_dwordx4 v132, s[58:59]
	s_waitcnt vmcnt(8)
	s_waitcnt lgkmcnt(0)
	v_mfma_f32_16x16x32_bf16 v[128:131], v[148:151], v[210:213], v[128:131]
	v_mfma_f32_16x16x32_bf16 v[124:127], v[186:189], v[210:213], v[124:127]
	v_mfma_f32_16x16x32_bf16 v[120:123], v[148:151], v[218:221], v[120:123]
	v_mfma_f32_16x16x32_bf16 v[116:119], v[186:189], v[218:221], v[116:119]
	s_barrier
	s_setprio 1
	s_waitcnt lgkmcnt(0)
	v_mfma_f32_16x16x32_bf16 v[80:83], v[148:151], v[226:229], v[80:83]
	v_mfma_f32_16x16x32_bf16 v[76:79], v[186:189], v[226:229], v[76:79]
	v_mfma_f32_16x16x32_bf16 v[72:75], v[148:151], v[234:237], v[72:75]
	v_mfma_f32_16x16x32_bf16 v[68:71], v[186:189], v[234:237], v[68:71]
	v_mfma_f32_16x16x32_bf16 v[128:131], v[152:155], v[214:217], v[128:131]
	v_mfma_f32_16x16x32_bf16 v[124:127], v[190:193], v[214:217], v[124:127]
	v_mfma_f32_16x16x32_bf16 v[120:123], v[152:155], v[222:225], v[120:123]
	v_mfma_f32_16x16x32_bf16 v[116:119], v[190:193], v[222:225], v[116:119]
	v_mfma_f32_16x16x32_bf16 v[80:83], v[152:155], v[230:233], v[80:83]
	v_mfma_f32_16x16x32_bf16 v[76:79], v[190:193], v[230:233], v[76:79]
	v_mfma_f32_16x16x32_bf16 v[72:75], v[152:155], v[238:241], v[72:75]
	v_mfma_f32_16x16x32_bf16 v[68:71], v[190:193], v[238:241], v[68:71]
	s_setprio 0
	s_setprio 1
	v_mfma_f32_16x16x32_bf16 v[112:115], v[194:197], v[210:213], v[112:115]
	v_mfma_f32_16x16x32_bf16 v[96:99], v[202:205], v[210:213], v[96:99]
	v_mfma_f32_16x16x32_bf16 v[108:111], v[194:197], v[218:221], v[108:111]
	v_mfma_f32_16x16x32_bf16 v[92:95], v[202:205], v[218:221], v[92:95]
	v_mfma_f32_16x16x32_bf16 v[64:67], v[194:197], v[226:229], v[64:67]
	v_mfma_f32_16x16x32_bf16 v[60:63], v[202:205], v[226:229], v[60:63]
	v_mfma_f32_16x16x32_bf16 v[56:59], v[194:197], v[234:237], v[56:59]
	v_mfma_f32_16x16x32_bf16 v[44:47], v[202:205], v[234:237], v[44:47]
	v_mfma_f32_16x16x32_bf16 v[112:115], v[198:201], v[214:217], v[112:115]
	v_mfma_f32_16x16x32_bf16 v[96:99], v[206:209], v[214:217], v[96:99]
	v_mfma_f32_16x16x32_bf16 v[108:111], v[198:201], v[222:225], v[108:111]
	v_mfma_f32_16x16x32_bf16 v[92:95], v[206:209], v[222:225], v[92:95]
	v_mfma_f32_16x16x32_bf16 v[64:67], v[198:201], v[230:233], v[64:67]
	v_mfma_f32_16x16x32_bf16 v[60:63], v[206:209], v[230:233], v[60:63]
	v_mfma_f32_16x16x32_bf16 v[56:59], v[198:201], v[238:241], v[56:59]
	v_mfma_f32_16x16x32_bf16 v[44:47], v[206:209], v[238:241], v[44:47]
	s_setprio 0
	s_barrier
	v_add_u32_e32 v157, s82, v146
	ds_read_b128 v[148:151], v157
	ds_read_b128 v[152:155], v157 offset:1024
	ds_read_b128 v[186:189], v157 offset:2048
	ds_read_b128 v[190:193], v157 offset:3072
	v_add_u32_e32 v157, s62, v146
	ds_read_b128 v[194:197], v157
	ds_read_b128 v[198:201], v157 offset:1024
	ds_read_b128 v[202:205], v157 offset:2048
	ds_read_b128 v[206:209], v157 offset:3072
	s_add_u32 s58, s58, 0x40000
	s_addc_u32 s59, s59, 0
	s_mov_b32 m0, s12
	ds_read_b128 v[210:213], v147 offset:32768
	ds_read_b128 v[214:217], v147 offset:33792
	ds_read_b128 v[218:221], v147 offset:34816
	ds_read_b128 v[222:225], v147 offset:35840
	ds_read_b128 v[226:229], v147 offset:36864
	ds_read_b128 v[230:233], v147 offset:37888
	ds_read_b128 v[234:237], v147 offset:38912
	ds_read_b128 v[238:241], v147 offset:39936
	global_load_lds_dwordx4 v2, s[58:59]
	s_mov_b32 m0, s13
	s_nop 0
	global_load_lds_dwordx4 v132, s[58:59]
	s_waitcnt vmcnt(8)
	s_waitcnt lgkmcnt(0)
	v_mfma_f32_16x16x32_bf16 v[36:39], v[148:151], v[210:213], v[36:39]
	v_mfma_f32_16x16x32_bf16 v[24:27], v[186:189], v[210:213], v[24:27]
	v_mfma_f32_16x16x32_bf16 v[40:43], v[148:151], v[218:221], v[40:43]
	v_mfma_f32_16x16x32_bf16 v[20:23], v[186:189], v[218:221], v[20:23]
	s_barrier
	s_setprio 1
	s_waitcnt lgkmcnt(0)
	v_mfma_f32_16x16x32_bf16 v[100:103], v[148:151], v[226:229], v[100:103]
	v_mfma_f32_16x16x32_bf16 v[88:91], v[186:189], v[226:229], v[88:91]
	v_mfma_f32_16x16x32_bf16 v[104:107], v[148:151], v[234:237], v[104:107]
	v_mfma_f32_16x16x32_bf16 v[84:87], v[186:189], v[234:237], v[84:87]
	v_mfma_f32_16x16x32_bf16 v[36:39], v[152:155], v[214:217], v[36:39]
	v_mfma_f32_16x16x32_bf16 v[24:27], v[190:193], v[214:217], v[24:27]
	v_mfma_f32_16x16x32_bf16 v[40:43], v[152:155], v[222:225], v[40:43]
	v_mfma_f32_16x16x32_bf16 v[20:23], v[190:193], v[222:225], v[20:23]
	v_mfma_f32_16x16x32_bf16 v[100:103], v[152:155], v[230:233], v[100:103]
	v_mfma_f32_16x16x32_bf16 v[88:91], v[190:193], v[230:233], v[88:91]
	v_mfma_f32_16x16x32_bf16 v[104:107], v[152:155], v[238:241], v[104:107]
	v_mfma_f32_16x16x32_bf16 v[84:87], v[190:193], v[238:241], v[84:87]
	s_setprio 0
	s_setprio 1
	v_mfma_f32_16x16x32_bf16 v[16:19], v[194:197], v[210:213], v[16:19]
	v_mfma_f32_16x16x32_bf16 v[8:11], v[202:205], v[210:213], v[8:11]
	v_mfma_f32_16x16x32_bf16 v[12:15], v[194:197], v[218:221], v[12:15]
	v_mfma_f32_16x16x32_bf16 v[4:7], v[202:205], v[218:221], v[4:7]
	v_mfma_f32_16x16x32_bf16 v[52:55], v[194:197], v[226:229], v[52:55]
	v_mfma_f32_16x16x32_bf16 v[32:35], v[202:205], v[226:229], v[32:35]
	v_mfma_f32_16x16x32_bf16 v[48:51], v[194:197], v[234:237], v[48:51]
	v_mfma_f32_16x16x32_bf16 v[28:31], v[202:205], v[234:237], v[28:31]
	v_mfma_f32_16x16x32_bf16 v[16:19], v[198:201], v[214:217], v[16:19]
	v_mfma_f32_16x16x32_bf16 v[8:11], v[206:209], v[214:217], v[8:11]
	v_mfma_f32_16x16x32_bf16 v[12:15], v[198:201], v[222:225], v[12:15]
	v_mfma_f32_16x16x32_bf16 v[4:7], v[206:209], v[222:225], v[4:7]
	v_mfma_f32_16x16x32_bf16 v[52:55], v[198:201], v[230:233], v[52:55]
	v_mfma_f32_16x16x32_bf16 v[32:35], v[206:209], v[230:233], v[32:35]
	v_mfma_f32_16x16x32_bf16 v[48:51], v[198:201], v[238:241], v[48:51]
	v_mfma_f32_16x16x32_bf16 v[28:31], v[206:209], v[238:241], v[28:31]
	s_setprio 0
	s_barrier
	s_add_i32 s28, s82, s9
	s_add_u32 s30, s30, 0x80
	s_addc_u32 s31, s31, 0
	s_add_u32 s58, s58, 0xfffc0080
	s_addc_u32 s59, s59, -1
	s_mov_b32 m0, s28
	ds_read_b128 v[210:213], v147 offset:49152
	ds_read_b128 v[214:217], v147 offset:50176
	ds_read_b128 v[218:221], v147 offset:51200
	ds_read_b128 v[222:225], v147 offset:52224
	ds_read_b128 v[226:229], v147 offset:53248
	ds_read_b128 v[230:233], v147 offset:54272
	ds_read_b128 v[234:237], v147 offset:55296
	ds_read_b128 v[238:241], v147 offset:56320
	global_load_lds_dwordx4 v2, s[30:31]
	s_add_i32 m0, s28, 0x2000
	s_add_i32 s28, s62, s9
	global_load_lds_dwordx4 v132, s[30:31]
	s_mov_b32 m0, s28
	s_nop 0
	global_load_lds_dwordx4 v134, s[30:31]
	s_add_i32 m0, s28, 0x2000
	s_nop 0
	global_load_lds_dwordx4 v0, s[30:31]
	s_mov_b32 m0, s15
	s_nop 0
	global_load_lds_dwordx4 v2, s[58:59]
	s_mov_b32 m0, s16
	s_nop 0
	global_load_lds_dwordx4 v132, s[58:59]
	s_waitcnt vmcnt(8)
	s_waitcnt lgkmcnt(0)
	v_mfma_f32_16x16x32_bf16 v[128:131], v[148:151], v[210:213], v[128:131]
	v_mfma_f32_16x16x32_bf16 v[124:127], v[186:189], v[210:213], v[124:127]
	v_mfma_f32_16x16x32_bf16 v[120:123], v[148:151], v[218:221], v[120:123]
	v_mfma_f32_16x16x32_bf16 v[116:119], v[186:189], v[218:221], v[116:119]
	s_barrier
	s_setprio 1
	s_waitcnt lgkmcnt(0)
	v_mfma_f32_16x16x32_bf16 v[80:83], v[148:151], v[226:229], v[80:83]
	v_mfma_f32_16x16x32_bf16 v[76:79], v[186:189], v[226:229], v[76:79]
	v_mfma_f32_16x16x32_bf16 v[72:75], v[148:151], v[234:237], v[72:75]
	v_mfma_f32_16x16x32_bf16 v[68:71], v[186:189], v[234:237], v[68:71]
	v_mfma_f32_16x16x32_bf16 v[128:131], v[152:155], v[214:217], v[128:131]
	v_mfma_f32_16x16x32_bf16 v[124:127], v[190:193], v[214:217], v[124:127]
	v_mfma_f32_16x16x32_bf16 v[120:123], v[152:155], v[222:225], v[120:123]
	v_mfma_f32_16x16x32_bf16 v[116:119], v[190:193], v[222:225], v[116:119]
	v_mfma_f32_16x16x32_bf16 v[80:83], v[152:155], v[230:233], v[80:83]
	v_mfma_f32_16x16x32_bf16 v[76:79], v[190:193], v[230:233], v[76:79]
	v_mfma_f32_16x16x32_bf16 v[72:75], v[152:155], v[238:241], v[72:75]
	v_mfma_f32_16x16x32_bf16 v[68:71], v[190:193], v[238:241], v[68:71]
	s_setprio 0
	s_setprio 1
	v_mfma_f32_16x16x32_bf16 v[112:115], v[194:197], v[210:213], v[112:115]
	v_mfma_f32_16x16x32_bf16 v[96:99], v[202:205], v[210:213], v[96:99]
	v_mfma_f32_16x16x32_bf16 v[108:111], v[194:197], v[218:221], v[108:111]
	v_mfma_f32_16x16x32_bf16 v[92:95], v[202:205], v[218:221], v[92:95]
	v_mfma_f32_16x16x32_bf16 v[64:67], v[194:197], v[226:229], v[64:67]
	v_mfma_f32_16x16x32_bf16 v[60:63], v[202:205], v[226:229], v[60:63]
	v_mfma_f32_16x16x32_bf16 v[56:59], v[194:197], v[234:237], v[56:59]
	v_mfma_f32_16x16x32_bf16 v[44:47], v[202:205], v[234:237], v[44:47]
	v_mfma_f32_16x16x32_bf16 v[112:115], v[198:201], v[214:217], v[112:115]
	v_mfma_f32_16x16x32_bf16 v[96:99], v[206:209], v[214:217], v[96:99]
	v_mfma_f32_16x16x32_bf16 v[108:111], v[198:201], v[222:225], v[108:111]
	v_mfma_f32_16x16x32_bf16 v[92:95], v[206:209], v[222:225], v[92:95]
	v_mfma_f32_16x16x32_bf16 v[64:67], v[198:201], v[230:233], v[64:67]
	v_mfma_f32_16x16x32_bf16 v[60:63], v[206:209], v[230:233], v[60:63]
	v_mfma_f32_16x16x32_bf16 v[56:59], v[198:201], v[238:241], v[56:59]
	v_mfma_f32_16x16x32_bf16 v[44:47], v[206:209], v[238:241], v[44:47]
	s_setprio 0
	s_barrier
	s_add_i32 s27, s27, 2
	s_add_u32 vcc_lo, vcc_lo, 0x100
	s_addc_u32 vcc_hi, vcc_hi, 0
	s_cmp_gt_u32 s27, 13
	s_cbranch_scc0 .LBB0_1201
	s_and_b64 vcc, exec, s[48:49]
	s_cbranch_vccz .LBB0_1204
	s_barrier
